# speedup vs baseline: 1.0095x; 1.0095x over previous
; __device__ __forceinline__ int opaque_v(int x) { asm volatile("" : "+v"(x)); return x; }
; __device__ __forceinline__ void sb_item(KParams p, int tb, int hd) {
;   bf16_t* Ks = (bf16_t*)smem;
;   bf16_t* Vts = Ks + LTILE;
;   const int tid = opaque_v(threadIdx.x);
;   const int lane = tid & 63, w = tid >> 6, fr = lane & 15, g = lane >> 4;
;   const int b = tb >> 6, i = tb & 63;
;   const int tok0 = tb * 128;
;   const int rt = (w < 4) ? w : 11 - w;
; __device__ __forceinline__ void phase_mixers(int l) {
;     ...
;   { KParams p = kparams(); for (int it = blockIdx.x; it < NBLK * 8; it += gridDim.x) sb_item(p, (NBLK - 1) - (it >> 3), it & 7); }
.LBB0_222:
	s_or_b64 exec, exec, s[0:1]
	v_readfirstlane_b32 s0, v192
	s_cmpk_lt_u32 s0, 0x100
	s_cbranch_scc1 .Lsb_prio_done
	s_setprio 1
.Lsb_prio_done:
	v_readlane_b32 s0, v255, 10
	v_readlane_b32 s34, v255, 12
	v_readlane_b32 s1, v255, 11
	v_readlane_b32 s35, v255, 13
	s_and_b64 vcc, exec, s[0:1]
	s_barrier
	s_cbranch_vccz .LBB0_296
	v_readlane_b32 s55, v255, 14
	s_branch .LBB0_225

; __device__ __forceinline__ int opaque_v(int x) { asm volatile("" : "+v"(x)); return x; }
; __device__ __forceinline__ void sb_item(KParams p, int tb, int hd) {
;   bf16_t* Ks = (bf16_t*)smem;
;   bf16_t* Vts = Ks + LTILE;
;   const int tid = opaque_v(threadIdx.x);
;   const int lane = tid & 63, w = tid >> 6, fr = lane & 15, g = lane >> 4;
;   const int b = tb >> 6, i = tb & 63;
;   const int tok0 = tb * 128;
;   const int rt = (w < 4) ? w : 11 - w;
;   const int qrow = rt * 16 + fr;
;   const size_t tok = (size_t)(tok0 + qrow);
;   const bf16_t* kbase = p->proj + C_KA + hd * 128;
;   const bf16_t* vbase = p->vt + (size_t)(VT_A + hd * 128) * T_TOK;
;   Tile4 kreg = tile_ld(kbase + (size_t)tok0 * NPROJ, NPROJ, tid);
;   Tile4 vreg = tile_ld(vbase + tok0, T_TOK, tid);
;   bf16x8 qf[4];
;   {
;     const bf16_t* qp = p->proj + tok * NPROJ + C_QA + hd * 128 + g * 8;
; #pragma unroll
;     for (int kc = 0; kc < 4; ++kc) qf[kc] = *(const bf16x8*)(qp + kc * 32);
;   }
;   f32x4 o[8];
; #pragma unroll
;   for (int dt = 0; dt < 8; ++dt) o[dt] = (f32x4){0.f, 0.f, 0.f, 0.f};
;   float carry = 0.f;
;   for (int j = i; j >= 0; --j) {
;     __syncthreads();
;     tile_st(kreg, Ks, tid); tile_st(vreg, Vts, tid);
;     __syncthreads();
;     {
;       const int ktok0 = (b * 64 + max(j - 1, 0)) * 128;
;       kreg = tile_ld(kbase + (size_t)ktok0 * NPROJ, NPROJ, tid);
.LBB0_225:
	v_mov_b32_e32 v172, v192
	s_load_dwordx4 s[4:7], s[34:35], 0x70
	s_ashr_i32 s0, s55, 3
	s_sub_i32 s12, 0x7f, s0
	s_and_b32 s81, s55, 7
	s_and_b32 s82, s12, 0x1fffffc0
	s_lshl_b32 s10, s12, 7
	s_lshl_b32 s88, s81, 8
	s_waitcnt lgkmcnt(0)
	s_add_u32 s8, s4, s88
	s_addc_u32 s9, s5, 0
	s_lshl_b32 s0, s81, 22
	s_add_u32 s0, s6, s0
	s_mov_b32 s11, s89
	s_addc_u32 s1, s7, 0
	v_ashrrev_i32_e32 v2, 4, v172
	s_and_b32 s83, s12, 63
	s_lshl_b64 s[6:7], s[10:11], 1
	v_ashrrev_i32_e32 v3, 31, v2
	s_add_u32 s6, s0, s6
	v_lshlrev_b64 v[52:53], 15, v[2:3]
	s_addc_u32 s7, s1, s7
	s_mul_i32 s12, s12, 0x360000
	v_lshl_add_u64 v[4:5], s[6:7], 0, v[52:53]
	s_mul_hi_u32 s7, s10, 0x6c00
	s_add_u32 s6, s8, s12
	s_addc_u32 s7, s9, s7
	v_lshlrev_b32_e32 v0, 4, v172
	v_mov_b64_e32 v[6:7], s[6:7]
	v_and_b32_e32 v50, 0xf0, v0
	v_mov_b32_e32 v51, v1
	v_mad_i64_i32 v[6:7], s[6:7], v2, s57, v[6:7]
	v_lshl_add_u64 v[6:7], v[6:7], 0, v[50:51]
	v_add_co_u32_e32 v8, vcc, s59, v6
	v_lshl_add_u64 v[4:5], v[4:5], 0, v[50:51]
	s_nop 0
	v_addc_co_u32_e32 v9, vcc, 0, v7, vcc
	global_load_dwordx4 v[18:21], v[6:7], off offset:2048
	global_load_dwordx4 v[22:25], v[8:9], off offset:2048
	v_add_co_u32_e32 v8, vcc, s64, v6
	s_mov_b32 s6, 0x300000
	s_nop 0
	v_addc_co_u32_e32 v9, vcc, 0, v7, vcc
	v_add_co_u32_e32 v6, vcc, s65, v6
	v_ashrrev_i32_e32 v3, 6, v172
	s_nop 0
	v_addc_co_u32_e32 v7, vcc, 0, v7, vcc
	global_load_dwordx4 v[26:29], v[8:9], off offset:2048
	global_load_dwordx4 v[30:33], v[6:7], off offset:2048
	global_load_dwordx4 v[34:37], v[4:5], off
	v_add_co_u32_e32 v6, vcc, s80, v4
	v_and_b32_e32 v56, 15, v172
	s_nop 0
	v_addc_co_u32_e32 v7, vcc, 0, v5, vcc
	v_add_co_u32_e32 v8, vcc, s74, v4
	v_lshl_add_u64 v[52:53], s[0:1], 0, v[52:53]
	s_nop 0
	v_addc_co_u32_e32 v9, vcc, 0, v5, vcc
	global_load_dwordx4 v[38:41], v[6:7], off
	global_load_dwordx4 v[42:45], v[8:9], off
	v_add_co_u32_e32 v4, vcc, s6, v4
	v_mov_b64_e32 v[6:7], s[8:9]
	s_nop 0
	v_addc_co_u32_e32 v5, vcc, 0, v5, vcc
	global_load_dwordx4 v[46:49], v[4:5], off
	v_sub_u32_e32 v4, 11, v3
	v_cmp_gt_i32_e32 vcc, 4, v3
	v_mul_lo_u32 v5, v2, s58
	v_add3_u32 v176, s45, v50, v5
	v_cndmask_b32_e32 v173, v4, v3, vcc
	v_lshl_or_b32 v82, v173, 4, v56
	v_add_u32_e32 v174, s10, v82
	v_mov_b64_e32 v[4:5], s[4:5]
	s_add_i32 s0, s83, -1
	v_bfe_u32 v57, v172, 4, 2
	v_mad_i64_i32 v[112:113], s[4:5], v174, s57, v[4:5]
	v_mad_i64_i32 v[54:55], s[4:5], v2, s57, v[6:7]
	s_max_i32 s0, s0, 0
	v_lshlrev_b32_e32 v0, 4, v57
	v_lshl_add_u64 v[4:5], v[112:113], 0, s[88:89]
	s_or_b32 s4, s0, s82
	v_lshl_add_u64 v[14:15], v[4:5], 0, v[0:1]
	v_lshl_add_u64 v[114:115], v[54:55], 0, v[50:51]
	s_lshl_b32 s0, s4, 7
	global_load_dwordx4 v[2:5], v[14:15], off
	global_load_dwordx4 v[6:9], v[14:15], off offset:64
	global_load_dwordx4 v[10:13], v[14:15], off offset:128
	s_nop 0
	global_load_dwordx4 v[14:17], v[14:15], off offset:192
	s_barrier
	v_lshl_add_u64 v[116:117], v[52:53], 0, v[50:51]
	s_lshl_b32 s88, s4, 8
	v_lshlrev_b32_e32 v175, 3, v57
	v_add_u32_e32 v50, 0x100, v0
	v_lshlrev_b32_e32 v0, 2, v172
	s_cmp_lg_u64 exec, 0
	v_add_u32_e32 v52, 64, v0
	v_bitop3_b32 v179, v0, s3, v195 bitop3:0x6c
	v_sub_u32_e32 v0, v50, v175
	v_mul_u32_u24_e32 v51, 0x110, v56
	v_mad_u32_u24 v181, v56, s58, v0
	v_mov_b32_e32 v53, 0
	v_lshlrev_b32_e32 v177, 2, v57
	s_waitcnt vmcnt(11)
	ds_write_b128 v176, v[18:21]
	s_waitcnt vmcnt(10)
	ds_write_b128 v176, v[22:25] offset:8704
	s_waitcnt vmcnt(9)
	ds_write_b128 v176, v[26:29] offset:17408
	s_waitcnt vmcnt(8)
	ds_write_b128 v176, v[30:33] offset:26112
	s_waitcnt vmcnt(7)
	ds_write_b128 v176, v[34:37] offset:34816
	s_waitcnt vmcnt(6)
	ds_write_b128 v176, v[38:41] offset:43520
	s_waitcnt vmcnt(5)
	ds_write_b128 v176, v[42:45] offset:52224
	s_waitcnt vmcnt(4)
	ds_write_b128 v176, v[46:49] offset:60928
	v_mad_u64_u32 v[26:27], s[0:1], s0, v196, v[114:115]
	v_add_co_u32_e32 v22, vcc, s59, v26
	v_lshl_add_u64 v[42:43], v[116:117], 0, s[88:89]
	s_nop 0
	v_addc_co_u32_e32 v23, vcc, 0, v27, vcc
	v_add_co_u32_e32 v28, vcc, s64, v26
	s_waitcnt lgkmcnt(0)
	s_nop 0
	v_addc_co_u32_e32 v29, vcc, 0, v27, vcc
	v_add_co_u32_e32 v30, vcc, s65, v26
	s_barrier
; __device__ __forceinline__ f32x4 mfma16(bf16x8 a, bf16x8 b, f32x4 c) { return __builtin_amdgcn_mfma_f32_16x16x32_bf16(a, b, c, 0, 0, 0); }
; __device__ __forceinline__ void qk_tiles(f32x4 (&s)[8], const bf16_t* Ks, const bf16x8 (&qf)[4], int fr, int g, int tlo, int thi) {
;   __builtin_amdgcn_s_setprio(1);
; #pragma unroll
;   for (int T = 0; T < 8; ++T) {
;     s[T] = (f32x4){0.f, 0.f, 0.f, 0.f};
;     if (T >= tlo && T <= thi) {
; #pragma unroll
;       for (int kc = 0; kc < 4; ++kc) {
;         bf16x8 a = *(const bf16x8*)(Ks + (T * 16 + fr) * LROW + kc * 32 + g * 8);
;         s[T] = mfma16(a, qf[kc], s[T]);
;       }
;     }
;   }
; __device__ __forceinline__ void sb_item(KParams p, int tb, int hd) {
;     ...
;       const int ktok0 = (b * 64 + max(j - 1, 0)) * 128;
;       kreg = tile_ld(kbase + (size_t)ktok0 * NPROJ, NPROJ, tid);
;       vreg = tile_ld(vbase + ktok0, T_TOK, tid);
;     }
;     const bool wave_live = __any(carry >= -160.f) != 0;
;     const int thi = wave_live ? ((j == i) ? rt : 7) : -1;
;     if (thi >= 0) {
;       f32x4 s[8];
;       qk_tiles(s, Ks, qf, fr, g, 0, thi);
	s_nop 0
	v_addc_co_u32_e32 v31, vcc, 0, v27, vcc
	v_add_co_u32_e32 v38, vcc, s80, v42
	s_nop 1
	v_addc_co_u32_e32 v39, vcc, 0, v43, vcc
	v_add_co_u32_e32 v44, vcc, s74, v42
	global_load_dwordx4 v[18:21], v[26:27], off offset:2048
	s_nop 0
	global_load_dwordx4 v[22:25], v[22:23], off offset:2048
	v_addc_co_u32_e32 v45, vcc, 0, v43, vcc
	v_add_co_u32_e32 v46, vcc, 0x300000, v42
	global_load_dwordx4 v[26:29], v[28:29], off offset:2048
	s_nop 0
	global_load_dwordx4 v[34:37], v[30:31], off offset:2048
	v_addc_co_u32_e32 v47, vcc, 0, v43, vcc
	global_load_dwordx4 v[30:33], v[42:43], off
	s_nop 0
	global_load_dwordx4 v[38:41], v[38:39], off
	s_nop 0
	global_load_dwordx4 v[42:45], v[44:45], off
	s_nop 0
	global_load_dwordx4 v[46:49], v[46:47], off
	s_cselect_b64 vcc, -1, 0
	v_cndmask_b32_e32 v0, -1, v173, vcc
	v_and_b32_e32 v178, 0xfc, v52
	v_cmp_eq_u32_e64 s[4:5], 3, v57
	v_cmp_gt_u32_e64 s[6:7], 2, v57
	v_lshlrev_b32_e32 v180, 2, v56
	v_cmp_lt_i32_e32 vcc, -1, v0
	v_add_u32_e32 v182, v50, v51
	v_mov_b32_e32 v52, v53
	v_mov_b32_e32 v51, v53
	v_mov_b32_e32 v50, v53
	v_mov_b32_e32 v57, v53
	v_mov_b32_e32 v56, v53
	v_mov_b32_e32 v55, v53
	v_mov_b32_e32 v54, v53
	v_mov_b32_e32 v61, v53
	v_mov_b32_e32 v60, v53
	v_mov_b32_e32 v59, v53
	v_mov_b32_e32 v58, v53
	v_mov_b32_e32 v65, v53
	v_mov_b32_e32 v64, v53
	v_mov_b32_e32 v63, v53
	v_mov_b32_e32 v62, v53
	v_mov_b32_e32 v69, v53
	v_mov_b32_e32 v68, v53
	v_mov_b32_e32 v67, v53
	v_mov_b32_e32 v66, v53
	v_mov_b32_e32 v73, v53
	v_mov_b32_e32 v72, v53
	v_mov_b32_e32 v71, v53
	v_mov_b32_e32 v70, v53
	v_mov_b32_e32 v77, v53
	v_mov_b32_e32 v76, v53
	v_mov_b32_e32 v75, v53
	v_mov_b32_e32 v74, v53
	v_mov_b32_e32 v81, v53
	v_mov_b32_e32 v80, v53
	v_mov_b32_e32 v79, v53
	v_mov_b32_e32 v78, v53
	v_mov_b32_e32 v118, v53
	s_and_saveexec_b64 s[0:1], vcc
	s_cbranch_execz .LBB0_273
	ds_read_b128 v[50:53], v182
	ds_read_b128 v[54:57], v182 offset:64
	v_mov_b32_e32 v62, 0
	v_cmp_eq_u32_e64 s[12:13], 0, v0
	v_cmp_ne_u32_e64 s[14:15], 0, v0
	s_waitcnt vmcnt(11) lgkmcnt(1)
	v_mfma_f32_16x16x32_bf16 v[50:53], v[50:53], v[2:5], 0
	s_waitcnt vmcnt(10) lgkmcnt(0)
	v_mfma_f32_16x16x32_bf16 v[50:53], v[54:57], v[6:9], v[50:53]
	ds_read_b128 v[54:57], v182 offset:128
	s_waitcnt vmcnt(9) lgkmcnt(0)
	v_mfma_f32_16x16x32_bf16 v[50:53], v[54:57], v[10:13], v[50:53]
	ds_read_b128 v[54:57], v182 offset:192
	s_waitcnt vmcnt(8) lgkmcnt(0)
	v_mfma_f32_16x16x32_bf16 v[50:53], v[54:57], v[14:17], v[50:53]
	v_mov_b32_e32 v54, 0
	v_mov_b32_e32 v55, v62
	v_mov_b32_e32 v56, v62
	v_mov_b32_e32 v57, v62
	s_and_saveexec_b64 s[8:9], s[14:15]
	s_cbranch_execz .LBB0_228
	ds_read_b128 v[54:57], v182 offset:4352
	ds_read_b128 v[58:61], v182 offset:4416
	s_waitcnt lgkmcnt(1)
	v_mfma_f32_16x16x32_bf16 v[54:57], v[54:57], v[2:5], 0
	s_waitcnt lgkmcnt(0)
	v_mfma_f32_16x16x32_bf16 v[54:57], v[58:61], v[6:9], v[54:57]
	ds_read_b128 v[58:61], v182 offset:4480
	s_waitcnt lgkmcnt(0)
	v_mfma_f32_16x16x32_bf16 v[54:57], v[58:61], v[10:13], v[54:57]
	ds_read_b128 v[58:61], v182 offset:4544
	s_waitcnt lgkmcnt(0)
	v_mfma_f32_16x16x32_bf16 v[54:57], v[58:61], v[14:17], v[54:57]

; __device__ __forceinline__ float ex2(float x) { return __builtin_amdgcn_exp2f(x); }
; __device__ __forceinline__ float lg2(float x) { return __builtin_amdgcn_logf(x); }
; __device__ __forceinline__ void qk_tiles(f32x4 (&s)[8], const bf16_t* Ks, const bf16x8 (&qf)[4], int fr, int g, int tlo, int thi) {
;     ...
;   __builtin_amdgcn_s_setprio(0);
; __device__ __forceinline__ void sb_item(KParams p, int tb, int hd) {
;     ...
;       for (int T = 0; T < 8; ++T) {
;         if (T <= thi) {
; #pragma unroll
;           for (int r = 0; r < 4; ++r) {
;             const float z2 = s[T][r] * C2;
;             const float sp = fmaxf(z2, 0.f) + lg2(1.f + ex2(-fabsf(z2)));
;             l1[T][r] = -sp;
;             s[T][r] = z2 - sp;
;           }
;         }
;       }
.LBB0_240:
	s_or_b64 exec, exec, s[38:39]
	s_and_saveexec_b64 s[38:39], s[14:15]
	s_cbranch_execz .LBB0_242
	v_pk_mul_f32 v[84:85], v[54:55], s[92:93] op_sel_hi:[1,0]
	v_pk_mul_f32 v[90:91], v[56:57], s[92:93] op_sel_hi:[1,0]
	v_exp_f32_e64 v0, -|v84|
	v_max_f32_e32 v86, 0, v85
	v_exp_f32_e64 v83, -|v85|
	v_exp_f32_e64 v85, -|v91|
	v_add_f32_e32 v0, 1.0, v0
	v_log_f32_e32 v88, v0
	v_exp_f32_e64 v0, -|v90|
	v_add_f32_e32 v83, 1.0, v83
	v_log_f32_e32 v92, v83
	v_max_f32_e32 v84, 0, v84
	v_add_f32_e32 v0, 1.0, v0
	v_log_f32_e32 v89, v0
	v_add_f32_e32 v0, 1.0, v85
	v_log_f32_e32 v93, v0
	v_max_f32_e32 v85, 0, v90
	v_max_f32_e32 v87, 0, v91
	v_pk_add_f32 v[84:85], v[84:85], v[88:89]
	v_pk_add_f32 v[86:87], v[86:87], v[92:93]
	v_mov_b32_e32 v88, v84
	v_mov_b32_e32 v89, v86
	v_pk_add_f32 v[94:95], v[84:85], 0 neg_lo:[1,1] neg_hi:[1,1]
	v_mov_b32_e32 v84, v85
	v_mov_b32_e32 v85, v87
	v_pk_fma_f32 v[54:55], v[54:55], s[92:93], v[88:89] op_sel_hi:[1,0,1] neg_lo:[0,0,1] neg_hi:[0,0,1]
	v_pk_fma_f32 v[56:57], v[56:57], s[92:93], v[84:85] op_sel_hi:[1,0,1] neg_lo:[0,0,1] neg_hi:[0,0,1]
	v_pk_add_f32 v[98:99], v[86:87], 0 neg_lo:[1,1] neg_hi:[1,1]

; __device__ __forceinline__ float shfl_lane(float x, int src_lane) { return __int_as_float(__builtin_amdgcn_ds_bpermute(src_lane << 2, __float_as_int(x))); }
; __device__ __forceinline__ f32x4 mfma16(bf16x8 a, bf16x8 b, f32x4 c) { return __builtin_amdgcn_mfma_f32_16x16x32_bf16(a, b, c, 0, 0, 0); }
; __device__ __forceinline__ void pv_tiles(f32x4 (&o)[8], const bf16_t* Vts, const bf16x8 (&pf)[4], int fr, int g, int tlo, int thi) {
;     ...
;   for (int kc = 0; kc < 4; ++kc) {
;     if (2 * kc + 1 >= tlo && 2 * kc <= thi) {
; #pragma unroll
;       for (int dt = 0; dt < 8; ++dt) {
;         const bf16_t* vp = Vts + (dt * 16 + fr) * LROW + kc * 32 + g * 4;
;         bf16x4 lo = *(const bf16x4*)vp, hi = *(const bf16x4*)(vp + 16);
;         bf16x8 a = __builtin_shufflevector(lo, hi, 0, 1, 2, 3, 4, 5, 6, 7);
;         o[dt] = mfma16(a, pf[kc], o[dt]);
;       }
;     }
; __device__ __forceinline__ void sb_item(KParams p, int tb, int hd) {
;     ...
;         const float fd = (float)(qrow - g * 4);
; #pragma unroll
;         for (int T = 0; T < 8; ++T) {
;           if (T <= thi) {
; #pragma unroll
;             for (int r = 0; r < 4; ++r) {
;               const float m01 = __saturatef(fd - (float)(T * 16 + r));
;               l1[T][r] *= m01;
;               s[T][r] += m01 * 1e30f - 1e30f;
;             }
;           }
;         }
;       }
;       float running = carry;
;       bf16x8 pf[4];
; #pragma unroll
;       for (int kc = 0; kc < 4; ++kc) pf[kc] = (bf16x8){0, 0, 0, 0, 0, 0, 0, 0};
; #pragma unroll
;       for (int T = 7; T >= 0; --T) {
;         if (T <= thi) {
;           const float x = (l1[T][0] + l1[T][1]) + (l1[T][2] + l1[T][3]);
;           float a = shfl_lane(x, (lane + 16) & 63); a = (g < 3) ? a : 0.f;
;           const float y1 = x + a;
;           float b2 = shfl_lane(y1, (lane + 32) & 63); b2 = (g < 2) ? b2 : 0.f;
;           const float incl = y1 + b2;
;           const float tt = shfl_lane(incl, fr);
;           float base = running + (incl - x);
;           const float w3 = ex2(s[T][3] + base); base += l1[T][3];
;           const float w2 = ex2(s[T][2] + base); base += l1[T][2];
;           const float w1 = ex2(s[T][1] + base); base += l1[T][1];
;           const float w0 = ex2(s[T][0] + base);
;           set_pf(pf, T, w0, w1, w2, w3);
;           running += tt;
;         }
;       }
;       carry = running;
;       pv_tiles(o, Vts, pf, fr, g, 0, thi);
.LBB0_268:
	s_or_b64 exec, exec, s[16:17]
	v_mul_f32_e32 v54, 0x3e0293ee, v50
	v_exp_f32_e64 v55, -|v54|
	v_mul_f32_e32 v56, 0x3e0293ee, v51
	v_exp_f32_e64 v57, -|v56|
	v_max_f32_e32 v54, 0, v54
	v_add_f32_e32 v55, 1.0, v55
	v_log_f32_e32 v59, v55
	v_mul_f32_e32 v58, 0x3e0293ee, v52
	v_max_f32_e32 v55, 0, v56
	v_add_f32_e32 v56, 1.0, v57
	v_add_f32_e32 v59, v54, v59
	v_fma_f32 v60, v50, s92, -v59
	v_exp_f32_e64 v50, -|v58|
	v_mul_f32_e32 v54, 0x3e0293ee, v53
	v_log_f32_e32 v57, v56
	v_exp_f32_e64 v56, -|v54|
	v_add_f32_e32 v50, 1.0, v50
	v_log_f32_e32 v50, v50
	v_max_f32_e32 v58, 0, v58
	v_add_f32_e32 v56, 1.0, v56
	v_log_f32_e32 v56, v56
	v_cmp_nlt_f32_e64 s[12:13], 1.0, v102
	v_add_f32_e32 v58, v58, v50
	v_max_f32_e32 v54, 0, v54
	v_cndmask_b32_e64 v50, 1.0, v102, s[12:13]
	v_cmp_lt_i32_e64 s[12:13], -1, v122
	v_pk_add_f32 v[54:55], v[54:55], v[56:57]
	v_fma_f32 v61, v52, s92, -v58
	v_cndmask_b32_e64 v62, 0, v50, s[12:13]
	v_add_f32_e32 v50, -2.0, v102
	v_cmp_nlt_f32_e64 s[12:13], 1.0, v50
	v_fma_f32 v56, v51, s92, -v55
	v_fma_f32 v57, v53, s92, -v54
	v_cndmask_b32_e64 v51, 1.0, v50, s[12:13]
	v_cmp_ngt_f32_e64 s[12:13], 0, v50
	s_nop 1
	v_cndmask_b32_e64 v63, 0, v51, s[12:13]
	s_mov_b32 s12, 0xc0400000
	s_mov_b32 s13, -1.0
	v_pk_add_f32 v[50:51], v[102:103], s[12:13]
	s_nop 0
	v_cmp_nlt_f32_e64 s[12:13], 1.0, v50
	s_nop 1
	v_cndmask_b32_e64 v52, 1.0, v50, s[12:13]
	v_cmp_nlt_f32_e64 s[12:13], 1.0, v51
	s_nop 1
	v_cndmask_b32_e64 v53, 1.0, v51, s[12:13]
	v_cmp_ngt_f32_e64 s[12:13], 0, v51
	s_nop 1
	v_cndmask_b32_e64 v51, 0, v53, s[12:13]
	v_cmp_ngt_f32_e64 s[12:13], 0, v50
	s_nop 1
	v_cndmask_b32_e64 v50, 0, v52, s[12:13]
	v_pk_mul_f32 v[52:53], v[50:51], v[54:55] neg_lo:[0,1] neg_hi:[0,1]
	v_fmamk_f32 v50, v50, 0x7149f2ca, v194
	v_fma_f32 v54, -v63, v58, v52
	v_fma_f32 v55, -v62, v59, v53
	v_add_f32_e32 v54, v54, v55
	ds_bpermute_b32 v55, v178, v54
	v_add_f32_e32 v50, v50, v57
	v_fmamk_f32 v59, v62, 0x7149f2ca, v194
	v_fmamk_f32 v62, v63, 0x7149f2ca, v194
	v_fmamk_f32 v51, v51, 0x7149f2ca, v194
	s_waitcnt lgkmcnt(0)
	v_cndmask_b32_e64 v55, v55, 0, s[4:5]
	v_add_f32_e32 v55, v54, v55
	ds_bpermute_b32 v64, v179, v55
	v_add_f32_e32 v59, v59, v60
	v_add_f32_e32 v51, v51, v56
	v_add_f32_e32 v56, v62, v61
	s_waitcnt lgkmcnt(0)
	v_cndmask_b32_e64 v57, 0, v64, s[6:7]
	v_add_f32_e32 v55, v55, v57
	v_sub_f32_e32 v54, v55, v54
	v_add_f32_e32 v54, v0, v54
	v_add_f32_e32 v52, v52, v54
	v_fma_f32 v57, v63, -v58, v52
	v_add_f32_e32 v53, v53, v57
	v_add_f32_e32 v53, v59, v53
	v_add_f32_e32 v51, v51, v57
	v_add_f32_e32 v52, v56, v52
	v_add_f32_e32 v50, v50, v54
	ds_bpermute_b32 v98, v180, v55
	v_exp_f32_e32 v53, v53
	v_exp_f32_e32 v51, v51
	v_exp_f32_e32 v52, v52
	v_exp_f32_e32 v50, v50
	v_cvt_pk_bf16_f32 v94, v53, v51
	v_cvt_pk_bf16_f32 v95, v52, v50
	v_add_u32_e32 v106, 0x8800, v181
	ds_read2_b64 v[50:53], v106 offset1:4
	v_add_u32_e32 v105, 0x9800, v181
	v_add_u32_e32 v104, 0xa800, v181
	v_add_u32_e32 v103, 0xb800, v181
	v_add_u32_e32 v102, 0xc800, v181
	v_add_u32_e32 v101, 0xd800, v181
	v_add_u32_e32 v100, 0xe800, v181
	v_add_u32_e32 v99, 0xf800, v181
	s_waitcnt lgkmcnt(0)
	v_mfma_f32_16x16x32_bf16 v[78:81], v[50:53], v[94:97], 0
	ds_read2_b64 v[50:53], v105 offset0:32 offset1:36
	s_waitcnt lgkmcnt(0)
	v_mfma_f32_16x16x32_bf16 v[74:77], v[50:53], v[94:97], 0
	ds_read2_b64 v[50:53], v104 offset0:64 offset1:68
	s_waitcnt lgkmcnt(0)
	v_mfma_f32_16x16x32_bf16 v[70:73], v[50:53], v[94:97], 0
	ds_read2_b64 v[50:53], v103 offset0:96 offset1:100
	s_waitcnt lgkmcnt(0)
	v_mfma_f32_16x16x32_bf16 v[66:69], v[50:53], v[94:97], 0
	ds_read2_b64 v[50:53], v102 offset0:128 offset1:132
	s_waitcnt lgkmcnt(0)
	v_mfma_f32_16x16x32_bf16 v[62:65], v[50:53], v[94:97], 0
	ds_read2_b64 v[50:53], v101 offset0:160 offset1:164
	s_waitcnt lgkmcnt(0)
	v_mfma_f32_16x16x32_bf16 v[58:61], v[50:53], v[94:97], 0
	ds_read2_b64 v[50:53], v100 offset0:192 offset1:196
	s_waitcnt lgkmcnt(0)
	v_mfma_f32_16x16x32_bf16 v[54:57], v[50:53], v[94:97], 0
	ds_read2_b64 v[50:53], v99 offset0:224 offset1:228
	s_waitcnt lgkmcnt(0)
	v_mfma_f32_16x16x32_bf16 v[50:53], v[50:53], v[94:97], 0
	s_and_saveexec_b64 s[12:13], s[10:11]
	s_cbranch_execz .LBB0_294
	ds_read2_b64 v[94:97], v106 offset0:8 offset1:12
	s_waitcnt lgkmcnt(0)
	v_mfma_f32_16x16x32_bf16 v[78:81], v[94:97], v[90:93], v[78:81]
	ds_read2_b64 v[94:97], v105 offset0:40 offset1:44
	s_waitcnt lgkmcnt(0)
	v_mfma_f32_16x16x32_bf16 v[74:77], v[94:97], v[90:93], v[74:77]
	ds_read2_b64 v[94:97], v104 offset0:72 offset1:76
	s_waitcnt lgkmcnt(0)
	v_mfma_f32_16x16x32_bf16 v[70:73], v[94:97], v[90:93], v[70:73]
	ds_read2_b64 v[94:97], v103 offset0:104 offset1:108
	s_waitcnt lgkmcnt(0)
	v_mfma_f32_16x16x32_bf16 v[66:69], v[94:97], v[90:93], v[66:69]
	ds_read2_b64 v[94:97], v102 offset0:136 offset1:140
	s_waitcnt lgkmcnt(0)
	v_mfma_f32_16x16x32_bf16 v[62:65], v[94:97], v[90:93], v[62:65]
	ds_read2_b64 v[94:97], v101 offset0:168 offset1:172
	s_waitcnt lgkmcnt(0)
	v_mfma_f32_16x16x32_bf16 v[58:61], v[94:97], v[90:93], v[58:61]
	ds_read2_b64 v[94:97], v100 offset0:200 offset1:204
	s_waitcnt lgkmcnt(0)
	v_mfma_f32_16x16x32_bf16 v[54:57], v[94:97], v[90:93], v[54:57]
	ds_read2_b64 v[94:97], v99 offset0:232 offset1:236
	s_waitcnt lgkmcnt(0)
	v_mfma_f32_16x16x32_bf16 v[50:53], v[94:97], v[90:93], v[50:53]
	s_or_b64 exec, exec, s[12:13]
	s_and_saveexec_b64 s[10:11], s[8:9]
	s_cbranch_execnz .LBB0_295

; __device__ __forceinline__ void sb_item(KParams p, int tb, int hd) {
;     ...
;       carry = running;
;       pv_tiles(o, Vts, pf, fr, g, 0, thi);
;     }
;     ...
;     if (__syncthreads_and(carry < -160.f)) break;
.LBB0_272:
	s_or_b64 exec, exec, s[8:9]
	v_add_f32_e32 v118, v0, v98
.LBB0_273:
	s_or_b64 exec, exec, s[0:1]
	global_load_ushort v83, v1, s[48:49]
	global_load_ushort v0, v1, s[50:51]
	v_cmp_gt_f32_e32 vcc, s72, v118
	v_mov_b32_e32 v85, -1
	s_lshl_b32 s12, s81, 7
	v_cndmask_b32_e64 v82, 0, 1, vcc
	s_waitcnt vmcnt(1)
	v_readfirstlane_b32 s1, v83
	v_mov_b32_e32 v83, -1
	s_waitcnt vmcnt(0)
	v_readfirstlane_b32 s0, v0
	s_mul_i32 s0, s41, s0
	v_mov_b32_dpp v83, v82 row_shl:1 row_mask:0xf bank_mask:0xf
	v_and_b32_e32 v84, v83, v82
	s_ashr_i32 s0, s0, 8
	s_mul_i32 s0, s0, s1
	v_mov_b32_dpp v85, v84 row_shl:2 row_mask:0xf bank_mask:0xf
	v_bitop3_b32 v82, v83, v85, v82 bitop3:0x80
	v_mov_b32_e32 v83, -1
	s_add_i32 s0, s0, 63
	s_bitcmp1_b32 exec_hi, 0
	v_mov_b32_dpp v83, v82 row_shl:4 row_mask:0xf bank_mask:0xf
	v_bitop3_b32 v84, v84, v83, v85 bitop3:0x80
	v_mov_b32_e32 v85, -1
	s_nop 1
	v_mov_b32_dpp v85, v84 row_shl:8 row_mask:0xf bank_mask:0xf
	v_bitop3_b32 v82, v82, v85, v83 bitop3:0x80
	v_mov_b32_e32 v83, -1
	s_nop 1
	v_mov_b32_dpp v83, v82 wave_shl:1 row_mask:0xf bank_mask:0xf
	v_mov_b32_e32 v82, -1
	s_nop 1
	v_mov_b32_dpp v82, v83 row_mirror row_mask:0xf bank_mask:0xf
	v_bitop3_b32 v82, v82, v84, v85 bitop3:0x80
	s_nop 0
	v_readlane_b32 s1, v82, 32
	s_cselect_b32 s1, s1, -1
	v_readlane_b32 s8, v82, 0
	s_and_b32 s10, s1, s8
	s_and_b32 s8, s0, 0xffffffc0
	s_cmp_lg_u32 s8, 64
	s_cselect_b64 s[0:1], -1, 0
	s_cmp_eq_u32 s8, 64
	v_mov_b32_e32 v82, s10
	s_cbranch_scc1 .LBB0_280
	v_mad_u32_u24 v82, v193, v0, v252
	v_mad_u64_u32 v[82:83], s[8:9], v82, s97, v[192:193]
	v_lshrrev_b32_e32 v83, 6, v82
	v_or_b32_e32 v83, v197, v83
	v_cmp_eq_u32_e32 vcc, 0, v83
	s_and_saveexec_b64 s[8:9], vcc
	v_mov_b32_e32 v83, s10
	ds_write_b32 v1, v83
	s_or_b64 exec, exec, s[8:9]
	v_cmp_eq_u32_e32 vcc, 0, v197
	v_cmp_lt_u32_e64 s[8:9], 63, v82
	s_and_b64 s[14:15], s[8:9], vcc
	s_waitcnt lgkmcnt(0)
	s_barrier
	s_and_saveexec_b64 s[8:9], s[14:15]
	s_cbranch_execz .LBB0_279
	v_mbcnt_lo_u32_b32 v82, exec_lo, 0
	v_mbcnt_hi_u32_b32 v82, exec_hi, v82
	v_cmp_eq_u32_e32 vcc, 0, v82
	s_and_b64 exec, exec, vcc
	v_mov_b32_e32 v82, s10
	ds_and_b32 v1, v82

; __device__ __forceinline__ f32x4 mfma16(bf16x8 a, bf16x8 b, f32x4 c) { return __builtin_amdgcn_mfma_f32_16x16x32_bf16(a, b, c, 0, 0, 0); }
; __device__ __forceinline__ void qk_tiles(f32x4 (&s)[8], const bf16_t* Ks, const bf16x8 (&qf)[4], int fr, int g, int tlo, int thi) {
;   __builtin_amdgcn_s_setprio(1);
; #pragma unroll
;   for (int T = 0; T < 8; ++T) {
;     s[T] = (f32x4){0.f, 0.f, 0.f, 0.f};
;     if (T >= tlo && T <= thi) {
; #pragma unroll
;       for (int kc = 0; kc < 4; ++kc) {
;         bf16x8 a = *(const bf16x8*)(Ks + (T * 16 + fr) * LROW + kc * 32 + g * 8);
;         s[T] = mfma16(a, qf[kc], s[T]);
;       }
;     }
;   }
; __device__ __forceinline__ void sb_item(KParams p, int tb, int hd) {
;     ...
;   for (int j = i; j >= 0; --j) {
;     __syncthreads();
;     tile_st(kreg, Ks, tid); tile_st(vreg, Vts, tid);
;     __syncthreads();
;     {
;       const int ktok0 = (b * 64 + max(j - 1, 0)) * 128;
;       kreg = tile_ld(kbase + (size_t)ktok0 * NPROJ, NPROJ, tid);
;       vreg = tile_ld(vbase + ktok0, T_TOK, tid);
;     }
;     const bool wave_live = __any(carry >= -160.f) != 0;
;     const int thi = wave_live ? ((j == i) ? rt : 7) : -1;
;     if (thi >= 0) {
;       f32x4 s[8];
;       qk_tiles(s, Ks, qf, fr, g, 0, thi);
.LBB0_284:
	s_add_i32 s10, s13, 1
	s_cmp_lt_i32 s10, 0
	s_cbranch_scc1 .LBB0_293
	s_max_i32 s10, s13, 0
	s_add_i32 s14, s10, s82
	s_lshl_b32 s10, s14, 7
	v_mad_u64_u32 v[82:83], s[10:11], s10, v196, v[114:115]
	s_barrier
	s_waitcnt vmcnt(7)
	ds_write_b128 v176, v[18:21]
	s_waitcnt vmcnt(6)
	ds_write_b128 v176, v[22:25] offset:8704
	s_waitcnt vmcnt(5)
	ds_write_b128 v176, v[26:29] offset:17408
	s_waitcnt vmcnt(4)
	ds_write_b128 v176, v[34:37] offset:26112
	v_add_co_u32_e32 v22, vcc, s59, v82
	s_lshl_b32 s88, s14, 8
	s_nop 0
	v_addc_co_u32_e32 v23, vcc, 0, v83, vcc
	v_add_co_u32_e32 v26, vcc, s64, v82
	s_waitcnt vmcnt(3)
	ds_write_b128 v176, v[30:33] offset:34816
	s_waitcnt vmcnt(2)
	ds_write_b128 v176, v[38:41] offset:43520
	s_waitcnt vmcnt(1)
	ds_write_b128 v176, v[42:45] offset:52224
	s_waitcnt vmcnt(0)
	ds_write_b128 v176, v[46:49] offset:60928
	v_addc_co_u32_e32 v27, vcc, 0, v83, vcc
	v_add_co_u32_e32 v30, vcc, s65, v82
	v_lshl_add_u64 v[84:85], v[116:117], 0, s[88:89]
	s_nop 0
	v_addc_co_u32_e32 v31, vcc, 0, v83, vcc
	v_add_co_u32_e32 v38, vcc, 0x100000, v84
	s_waitcnt lgkmcnt(0)
	s_nop 0
	v_addc_co_u32_e32 v39, vcc, 0, v85, vcc
	v_add_co_u32_e32 v42, vcc, 0x200000, v84
	s_barrier
	s_nop 0
	v_addc_co_u32_e32 v43, vcc, 0, v85, vcc
	v_add_co_u32_e32 v46, vcc, 0x300000, v84
	s_nop 1
	v_addc_co_u32_e32 v47, vcc, 0, v85, vcc
	global_load_dwordx4 v[18:21], v[82:83], off offset:2048
	s_nop 0
	global_load_dwordx4 v[22:25], v[22:23], off offset:2048
	s_nop 0
	global_load_dwordx4 v[26:29], v[26:27], off offset:2048
	s_nop 0
	global_load_dwordx4 v[34:37], v[30:31], off offset:2048
	s_nop 0
	global_load_dwordx4 v[30:33], v[84:85], off
	s_nop 0
	global_load_dwordx4 v[38:41], v[38:39], off
	s_nop 0
	global_load_dwordx4 v[42:45], v[42:43], off
	v_cmp_le_f32_e32 vcc, s72, v118
	global_load_dwordx4 v[46:49], v[46:47], off
	s_cbranch_vccz .LBB0_287
	ds_read_b128 v[82:85], v182
	ds_read_b128 v[86:89], v182 offset:64
	s_waitcnt lgkmcnt(1)
	v_mfma_f32_16x16x32_bf16 v[82:85], v[82:85], v[2:5], 0
	ds_read_b128 v[90:93], v182 offset:4416
	ds_read_b128 v[94:97], v182 offset:8768
	ds_read_b128 v[98:101], v182 offset:13120
	s_waitcnt lgkmcnt(3)
	v_mfma_f32_16x16x32_bf16 v[82:85], v[86:89], v[6:9], v[82:85]
	ds_read_b128 v[86:89], v182 offset:128
	ds_read_b128 v[104:107], v182 offset:17472
	ds_read_b128 v[108:111], v182 offset:21824
	s_waitcnt lgkmcnt(2)
	v_mfma_f32_16x16x32_bf16 v[82:85], v[86:89], v[10:13], v[82:85]
	ds_read_b128 v[86:89], v182 offset:192
	ds_read_b128 v[120:123], v182 offset:26176
	ds_read_b128 v[124:127], v182 offset:30528
	s_waitcnt lgkmcnt(2)
	v_mfma_f32_16x16x32_bf16 v[82:85], v[86:89], v[14:17], v[82:85]
	ds_read_b128 v[86:89], v182 offset:4352
	s_waitcnt lgkmcnt(0)
	v_mfma_f32_16x16x32_bf16 v[86:89], v[86:89], v[2:5], 0
	v_mfma_f32_16x16x32_bf16 v[86:89], v[90:93], v[6:9], v[86:89]
	ds_read_b128 v[90:93], v182 offset:4480
	s_waitcnt lgkmcnt(0)
	v_mfma_f32_16x16x32_bf16 v[86:89], v[90:93], v[10:13], v[86:89]
	ds_read_b128 v[90:93], v182 offset:4544
	s_waitcnt lgkmcnt(0)
	v_mfma_f32_16x16x32_bf16 v[86:89], v[90:93], v[14:17], v[86:89]
	ds_read_b128 v[90:93], v182 offset:8704
	s_waitcnt lgkmcnt(0)
	v_mfma_f32_16x16x32_bf16 v[90:93], v[90:93], v[2:5], 0
	v_mfma_f32_16x16x32_bf16 v[90:93], v[94:97], v[6:9], v[90:93]
	ds_read_b128 v[94:97], v182 offset:8832
	s_waitcnt lgkmcnt(0)
	v_mfma_f32_16x16x32_bf16 v[90:93], v[94:97], v[10:13], v[90:93]
	ds_read_b128 v[94:97], v182 offset:8896
	s_waitcnt lgkmcnt(0)
	v_mfma_f32_16x16x32_bf16 v[90:93], v[94:97], v[14:17], v[90:93]
	ds_read_b128 v[94:97], v182 offset:13056
	s_waitcnt lgkmcnt(0)
	v_mfma_f32_16x16x32_bf16 v[94:97], v[94:97], v[2:5], 0
	v_mfma_f32_16x16x32_bf16 v[94:97], v[98:101], v[6:9], v[94:97]
	ds_read_b128 v[98:101], v182 offset:13184
	s_waitcnt lgkmcnt(0)
	v_mfma_f32_16x16x32_bf16 v[94:97], v[98:101], v[10:13], v[94:97]
	ds_read_b128 v[98:101], v182 offset:13248
	s_waitcnt lgkmcnt(0)
	v_mfma_f32_16x16x32_bf16 v[96:99], v[98:101], v[14:17], v[94:97]
	ds_read_b128 v[100:103], v182 offset:17408
	s_waitcnt lgkmcnt(0)
	v_mfma_f32_16x16x32_bf16 v[100:103], v[100:103], v[2:5], 0
	v_mfma_f32_16x16x32_bf16 v[100:103], v[104:107], v[6:9], v[100:103]
	ds_read_b128 v[104:107], v182 offset:17536
	s_waitcnt lgkmcnt(0)
	v_mfma_f32_16x16x32_bf16 v[100:103], v[104:107], v[10:13], v[100:103]
	ds_read_b128 v[104:107], v182 offset:17600
	s_waitcnt lgkmcnt(0)
	v_mfma_f32_16x16x32_bf16 v[100:103], v[104:107], v[14:17], v[100:103]
	ds_read_b128 v[104:107], v182 offset:21760
	s_waitcnt lgkmcnt(0)
	v_mfma_f32_16x16x32_bf16 v[104:107], v[104:107], v[2:5], 0
	v_mfma_f32_16x16x32_bf16 v[104:107], v[108:111], v[6:9], v[104:107]
	ds_read_b128 v[108:111], v182 offset:21888
	s_waitcnt lgkmcnt(0)
	v_mfma_f32_16x16x32_bf16 v[104:107], v[108:111], v[10:13], v[104:107]
	ds_read_b128 v[108:111], v182 offset:21952
	s_waitcnt lgkmcnt(0)
	v_mfma_f32_16x16x32_bf16 v[104:107], v[108:111], v[14:17], v[104:107]
	ds_read_b128 v[108:111], v182 offset:26112
	s_waitcnt lgkmcnt(0)
	v_mfma_f32_16x16x32_bf16 v[108:111], v[108:111], v[2:5], 0
	v_mfma_f32_16x16x32_bf16 v[108:111], v[120:123], v[6:9], v[108:111]
	ds_read_b128 v[120:123], v182 offset:26240
	s_waitcnt lgkmcnt(0)
	v_mfma_f32_16x16x32_bf16 v[108:111], v[120:123], v[10:13], v[108:111]
	ds_read_b128 v[120:123], v182 offset:26304
	s_waitcnt lgkmcnt(0)
	v_mfma_f32_16x16x32_bf16 v[108:111], v[120:123], v[14:17], v[108:111]
	ds_read_b128 v[120:123], v182 offset:30464
	s_waitcnt lgkmcnt(0)
	v_mfma_f32_16x16x32_bf16 v[120:123], v[120:123], v[2:5], 0
	v_mfma_f32_16x16x32_bf16 v[120:123], v[124:127], v[6:9], v[120:123]
	ds_read_b128 v[124:127], v182 offset:30592
	s_waitcnt lgkmcnt(0)
; __device__ __forceinline__ float shfl_lane(float x, int src_lane) { return __int_as_float(__builtin_amdgcn_ds_bpermute(src_lane << 2, __float_as_int(x))); }
; __device__ __forceinline__ float ex2(float x) { return __builtin_amdgcn_exp2f(x); }
; __device__ __forceinline__ float lg2(float x) { return __builtin_amdgcn_logf(x); }
; __device__ __forceinline__ void sb_item(KParams p, int tb, int hd) {
;     ...
;       float l1[8][4];
; #pragma unroll
;       for (int T = 0; T < 8; ++T) {
;         if (T <= thi) {
; #pragma unroll
;           for (int r = 0; r < 4; ++r) {
;             const float z2 = s[T][r] * C2;
;             const float sp = fmaxf(z2, 0.f) + lg2(1.f + ex2(-fabsf(z2)));
;             l1[T][r] = -sp;
;             s[T][r] = z2 - sp;
;           }
;         }
;       }
;     ...
;       for (int T = 7; T >= 0; --T) {
;         if (T <= thi) {
;           const float x = (l1[T][0] + l1[T][1]) + (l1[T][2] + l1[T][3]);
;           float a = shfl_lane(x, (lane + 16) & 63); a = (g < 3) ? a : 0.f;
;           const float y1 = x + a;
;           float b2 = shfl_lane(y1, (lane + 32) & 63); b2 = (g < 2) ? b2 : 0.f;
;           const float incl = y1 + b2;
;           const float tt = shfl_lane(incl, fr);
;           float base = running + (incl - x);
;           const float w3 = ex2(s[T][3] + base); base += l1[T][3];
;           const float w2 = ex2(s[T][2] + base); base += l1[T][2];
;           const float w1 = ex2(s[T][1] + base); base += l1[T][1];
;           const float w0 = ex2(s[T][0] + base);
	v_mfma_f32_16x16x32_bf16 v[120:123], v[124:127], v[10:13], v[120:123]
	ds_read_b128 v[124:127], v182 offset:30656
	s_waitcnt lgkmcnt(0)
	v_mfma_f32_16x16x32_bf16 v[184:187], v[124:127], v[14:17], v[120:123]
	s_nop 3
	v_mul_f32_e32 v120, 0x3e0293ee, v83
	v_mul_f32_e32 v82, 0x3e0293ee, v82
	v_exp_f32_e64 v83, -|v120|
	v_exp_f32_e64 v94, -|v82|
	v_mul_f32_e32 v122, 0x3e0293ee, v84
	v_mul_f32_e32 v84, 0x3e0293ee, v85
	v_add_f32_e32 v83, 1.0, v83
	v_add_f32_e32 v94, 1.0, v94
	v_log_f32_e32 v133, v83
	v_exp_f32_e64 v83, -|v122|
	v_log_f32_e32 v135, v94
	v_exp_f32_e64 v94, -|v84|
	v_mul_f32_e32 v124, 0x3e0293ee, v86
	v_add_f32_e32 v83, 1.0, v83
	v_log_f32_e32 v134, v83
	v_add_f32_e32 v83, 1.0, v94
	v_log_f32_e32 v132, v83
	v_exp_f32_e64 v83, -|v124|
	v_mul_f32_e32 v126, 0x3e0293ee, v87
	v_max_f32_e32 v128, 0, v84
	v_exp_f32_e64 v84, -|v126|
	v_add_f32_e32 v83, 1.0, v83
	v_log_f32_e32 v143, v83
	v_mul_f32_e32 v88, 0x3e0293ee, v88
	v_add_f32_e32 v83, 1.0, v84
	v_log_f32_e32 v141, v83
	v_exp_f32_e64 v83, -|v88|
	v_mul_f32_e32 v84, 0x3e0293ee, v89
	v_exp_f32_e64 v94, -|v84|
	v_mul_f32_e32 v90, 0x3e0293ee, v90
	v_add_f32_e32 v83, 1.0, v83
	v_log_f32_e32 v142, v83
	v_add_f32_e32 v83, 1.0, v94
	v_log_f32_e32 v140, v83
	v_exp_f32_e64 v83, -|v90|
	v_mul_f32_e32 v136, 0x3e0293ee, v91
	v_max_f32_e32 v86, 0, v84
	v_exp_f32_e64 v84, -|v136|
	v_add_f32_e32 v83, 1.0, v83
	v_log_f32_e32 v153, v83
	v_mul_f32_e32 v92, 0x3e0293ee, v92
	v_add_f32_e32 v83, 1.0, v84
	v_log_f32_e32 v151, v83
	v_exp_f32_e64 v83, -|v92|
	v_mul_f32_e32 v84, 0x3e0293ee, v93
	v_exp_f32_e64 v91, -|v84|
	v_mul_f32_e32 v154, 0x3e0293ee, v96
	v_add_f32_e32 v83, 1.0, v83
	v_log_f32_e32 v152, v83
	v_add_f32_e32 v83, 1.0, v91
	v_log_f32_e32 v150, v83
	v_exp_f32_e64 v83, -|v154|
	v_mul_f32_e32 v156, 0x3e0293ee, v97
	v_max_f32_e32 v148, 0, v84
	v_exp_f32_e64 v84, -|v156|
	v_add_f32_e32 v83, 1.0, v83
	v_log_f32_e32 v167, v83
	v_mul_f32_e32 v158, 0x3e0293ee, v98
	v_add_f32_e32 v83, 1.0, v84
	v_log_f32_e32 v165, v83
	v_exp_f32_e64 v83, -|v158|
	v_mul_f32_e32 v84, 0x3e0293ee, v99
	v_exp_f32_e64 v91, -|v84|
	v_mul_f32_e32 v98, 0x3e0293ee, v100
	v_add_f32_e32 v83, 1.0, v83
	v_log_f32_e32 v166, v83
	v_add_f32_e32 v83, 1.0, v91
	v_log_f32_e32 v164, v83
	v_exp_f32_e64 v83, -|v98|
	v_mul_f32_e32 v100, 0x3e0293ee, v101
	v_max_f32_e32 v162, 0, v84
	v_exp_f32_e64 v84, -|v100|
	v_add_f32_e32 v83, 1.0, v83
	v_log_f32_e32 v146, v83
	v_mul_f32_e32 v102, 0x3e0293ee, v102
	v_add_f32_e32 v83, 1.0, v84
	v_log_f32_e32 v188, v83
	v_exp_f32_e64 v83, -|v102|
	v_mul_f32_e32 v84, 0x3e0293ee, v103
	v_exp_f32_e64 v91, -|v84|
	v_mul_f32_e32 v104, 0x3e0293ee, v104
	v_add_f32_e32 v83, 1.0, v83
	v_log_f32_e32 v147, v83
	v_add_f32_e32 v83, 1.0, v91
	v_log_f32_e32 v189, v83
	v_exp_f32_e64 v83, -|v104|
	v_mul_f32_e32 v168, 0x3e0293ee, v105
	v_max_f32_e32 v171, 0, v84
	v_exp_f32_e64 v84, -|v168|
	v_add_f32_e32 v83, 1.0, v83
	v_log_f32_e32 v200, v83
	v_mul_f32_e32 v106, 0x3e0293ee, v106
	v_add_f32_e32 v83, 1.0, v84
	v_log_f32_e32 v204, v83
	v_exp_f32_e64 v83, -|v106|
	v_mul_f32_e32 v84, 0x3e0293ee, v107
	v_exp_f32_e64 v91, -|v84|
	v_mul_f32_e32 v108, 0x3e0293ee, v108
	v_add_f32_e32 v83, 1.0, v83
	v_log_f32_e32 v201, v83
	v_add_f32_e32 v83, 1.0, v91
	v_log_f32_e32 v205, v83
	v_exp_f32_e64 v83, -|v108|
	v_mul_f32_e32 v206, 0x3e0293ee, v109
	v_max_f32_e32 v203, 0, v84
	v_exp_f32_e64 v84, -|v206|
	v_add_f32_e32 v83, 1.0, v83
	v_mul_f32_e32 v184, 0x3e0293ee, v184
	v_log_f32_e32 v208, v83
	v_add_f32_e32 v83, 1.0, v84
	v_exp_f32_e64 v84, -|v184|
	v_mul_f32_e32 v216, 0x3e0293ee, v185
	v_exp_f32_e64 v91, -|v216|
	v_mul_f32_e32 v186, 0x3e0293ee, v186
	v_add_f32_e32 v84, 1.0, v84
	v_log_f32_e32 v218, v84
	v_add_f32_e32 v84, 1.0, v91
	v_exp_f32_e64 v91, -|v186|
	v_mul_f32_e32 v101, 0x3e0293ee, v187
	v_exp_f32_e64 v105, -|v101|
	v_log_f32_e32 v222, v84
	v_add_f32_e32 v84, 1.0, v91
	v_log_f32_e32 v219, v84
	v_add_f32_e32 v84, 1.0, v105
	v_log_f32_e32 v223, v84
	v_max_f32_e32 v214, 0, v184
	v_max_f32_e32 v220, 0, v216
	v_max_f32_e32 v215, 0, v186
	v_max_f32_e32 v221, 0, v101
	v_pk_add_f32 v[214:215], v[214:215], v[218:219]
	v_pk_add_f32 v[218:219], v[220:221], v[222:223]
	v_mul_f32_e32 v110, 0x3e0293ee, v110
	v_pk_add_f32 v[220:221], v[218:219], v[214:215] neg_lo:[1,1] neg_hi:[1,1]
	v_log_f32_e32 v212, v83
	v_add_f32_e32 v84, v220, v221
	ds_bpermute_b32 v91, v178, v84
	v_exp_f32_e64 v83, -|v110|
	v_mov_b32_e32 v220, v215
	v_mov_b32_e32 v221, v219
	v_max_f32_e32 v96, 0, v108
	s_waitcnt lgkmcnt(0)
	v_cndmask_b32_e64 v91, v91, 0, s[4:5]
	v_add_f32_e32 v83, 1.0, v83
	v_add_f32_e32 v91, v91, v84
	v_log_f32_e32 v209, v83
	v_mul_f32_e32 v83, 0x3e0293ee, v111
	ds_bpermute_b32 v105, v179, v91
	v_exp_f32_e64 v101, -|v83|
	v_max_f32_e32 v211, 0, v83
	v_max_f32_e32 v210, 0, v206
	v_max_f32_e32 v97, 0, v110
	v_add_f32_e32 v83, 1.0, v101
	s_waitcnt lgkmcnt(0)
	v_cndmask_b32_e64 v101, 0, v105, s[6:7]
	v_add_f32_e32 v91, v101, v91
	v_sub_f32_e32 v84, v91, v84
	v_log_f32_e32 v213, v83
	v_fma_f32 v83, v187, s92, -v219
	v_add_f32_e32 v187, v118, v84
	v_add_f32_e32 v83, v83, v187
	v_pk_add_f32 v[186:187], v[186:187], v[220:221] neg_lo:[0,1] neg_hi:[0,1]
	v_mov_b32_e32 v219, v215
	v_mov_b32_e32 v217, v187
	v_add_f32_e32 v84, v186, v187
	v_pk_add_f32 v[186:187], v[216:217], v[218:219] neg_lo:[0,1] neg_hi:[0,1]
	v_mov_b32_e32 v215, v218
	v_add_f32_e32 v101, v186, v187
	v_mov_b32_e32 v185, v187
	v_pk_add_f32 v[186:187], v[96:97], v[208:209]
	v_pk_add_f32 v[208:209], v[210:211], v[212:213]
	v_exp_f32_e32 v83, v83
	v_pk_add_f32 v[96:97], v[208:209], v[186:187] neg_lo:[1,1] neg_hi:[1,1]
	v_exp_f32_e32 v84, v84
	v_pk_add_f32 v[210:211], v[96:97], v[96:97] op_sel:[0,1] op_sel_hi:[1,0]
	ds_bpermute_b32 v105, v178, v210
	v_pk_add_f32 v[96:97], v[184:185], v[214:215] neg_lo:[0,1] neg_hi:[0,1]
	ds_bpermute_b32 v184, v180, v91
	v_add_f32_e32 v96, v96, v97
	v_exp_f32_e32 v101, v101
	s_waitcnt lgkmcnt(1)
; __device__ __forceinline__ unsigned pk2(float lo, float hi) { hwf2 v = {lo, hi}; return __builtin_bit_cast(unsigned, __builtin_convertvector(v, hwbf2)); }
; __device__ __forceinline__ float shfl_lane(float x, int src_lane) { return __int_as_float(__builtin_amdgcn_ds_bpermute(src_lane << 2, __float_as_int(x))); }
; __device__ __forceinline__ float ex2(float x) { return __builtin_amdgcn_exp2f(x); }
; __device__ __forceinline__ void set_pf(bf16x8 (&pf)[4], int T, float w0, float w1, float w2, float w3) {
;   unsigned lo = pk2(w0, w1), hi = pk2(w2, w3);
;   const int kc = T >> 1, h = (T & 1) * 4;
;   pf[kc][h + 0] = (short)(lo & 0xffff); pf[kc][h + 1] = (short)(lo >> 16);
;   pf[kc][h + 2] = (short)(hi & 0xffff); pf[kc][h + 3] = (short)(hi >> 16);
; }
; __device__ __forceinline__ void sb_item(KParams p, int tb, int hd) {
;     ...
;       for (int T = 7; T >= 0; --T) {
;         if (T <= thi) {
;           const float x = (l1[T][0] + l1[T][1]) + (l1[T][2] + l1[T][3]);
;           float a = shfl_lane(x, (lane + 16) & 63); a = (g < 3) ? a : 0.f;
;           const float y1 = x + a;
;           float b2 = shfl_lane(y1, (lane + 32) & 63); b2 = (g < 2) ? b2 : 0.f;
;           const float incl = y1 + b2;
;           const float tt = shfl_lane(incl, fr);
;           float base = running + (incl - x);
;           const float w3 = ex2(s[T][3] + base); base += l1[T][3];
;           const float w2 = ex2(s[T][2] + base); base += l1[T][2];
;           const float w1 = ex2(s[T][1] + base); base += l1[T][1];
;           const float w0 = ex2(s[T][0] + base);
;           set_pf(pf, T, w0, w1, w2, w3);
;           running += tt;
;         }
;       }
	v_cndmask_b32_e64 v97, v105, 0, s[4:5]
	v_add_f32_e32 v119, v210, v97
	ds_bpermute_b32 v105, v179, v119
	v_cvt_pk_bf16_f32 v97, v84, v83
	v_fma_f32 v83, v111, s92, -v209
	v_exp_f32_e32 v96, v96
	v_max_f32_e32 v190, 0, v104
	s_waitcnt lgkmcnt(0)
	v_cndmask_b32_e64 v185, 0, v105, s[6:7]
	v_pk_add_f32 v[118:119], v[118:119], v[184:185]
	v_max_f32_e32 v202, 0, v168
	v_pk_add_f32 v[210:211], v[118:119], v[210:211] op_sel:[1,0] op_sel_hi:[0,1] neg_lo:[0,1] neg_hi:[0,1]
	v_pk_add_f32 v[210:211], v[118:119], v[210:211]
	v_max_f32_e32 v191, 0, v106
	v_add_f32_e32 v83, v83, v210
	v_mov_b32_e32 v111, v210
	v_mov_b32_e32 v210, v187
	v_mov_b32_e32 v211, v209
	v_pk_add_f32 v[110:111], v[110:111], v[210:211] neg_lo:[0,1] neg_hi:[0,1]
	v_mov_b32_e32 v209, v187
	v_mov_b32_e32 v207, v111
	v_add_f32_e32 v84, v110, v111
	v_pk_add_f32 v[110:111], v[206:207], v[208:209] neg_lo:[0,1] neg_hi:[0,1]
	v_mov_b32_e32 v187, v208
	v_add_f32_e32 v91, v110, v111
	v_mov_b32_e32 v109, v111
	v_pk_add_f32 v[110:111], v[190:191], v[200:201]
	v_pk_add_f32 v[190:191], v[202:203], v[204:205]
	v_pk_add_f32 v[108:109], v[108:109], v[186:187] neg_lo:[0,1] neg_hi:[0,1]
	v_pk_add_f32 v[200:201], v[190:191], v[110:111] neg_lo:[1,1] neg_hi:[1,1]
	v_max_f32_e32 v94, 0, v98
	v_max_f32_e32 v170, 0, v100
	v_max_f32_e32 v95, 0, v102
	v_cvt_pk_bf16_f32 v96, v96, v101
	v_add_f32_e32 v101, v200, v201
	v_add_f32_e32 v108, v108, v109
	ds_bpermute_b32 v184, v180, v119
	ds_bpermute_b32 v105, v178, v101
	v_exp_f32_e32 v119, v108
	v_pk_add_f32 v[108:109], v[94:95], v[146:147]
	v_pk_add_f32 v[146:147], v[170:171], v[188:189]
	v_exp_f32_e32 v91, v91
	v_pk_add_f32 v[94:95], v[146:147], v[108:109] neg_lo:[1,1] neg_hi:[1,1]
	s_waitcnt lgkmcnt(0)
	v_cndmask_b32_e64 v105, v105, 0, s[4:5]
	v_add_f32_e32 v123, v94, v95
	ds_bpermute_b32 v125, v178, v123
	v_exp_f32_e32 v83, v83
	v_exp_f32_e32 v84, v84
	v_add_f32_e32 v105, v101, v105
	ds_bpermute_b32 v121, v179, v105
	v_cvt_pk_bf16_f32 v94, v119, v91
	s_waitcnt lgkmcnt(1)
	v_cndmask_b32_e64 v91, v125, 0, s[4:5]
	v_add_f32_e32 v91, v123, v91
	v_max_f32_e32 v161, 0, v154
	v_max_f32_e32 v163, 0, v156
	v_max_f32_e32 v160, 0, v158
	v_cvt_pk_bf16_f32 v95, v84, v83
	v_fma_f32 v83, v107, s92, -v191
	ds_bpermute_b32 v107, v179, v91
	v_pk_add_f32 v[160:161], v[160:161], v[166:167]
	v_pk_add_f32 v[162:163], v[162:163], v[164:165]
	s_waitcnt lgkmcnt(1)
	v_cndmask_b32_e64 v84, 0, v121, s[6:7]
	v_pk_add_f32 v[164:165], v[160:161], v[162:163] neg_lo:[1,1] neg_hi:[1,1]
	v_add_f32_e32 v84, v105, v84
	v_mov_b32_e32 v119, v164
	v_mov_b32_e32 v185, v165
	ds_bpermute_b32 v170, v180, v84
	v_sub_f32_e32 v84, v84, v101
	v_pk_add_f32 v[118:119], v[118:119], v[184:185]
	v_fma_f32 v101, v103, s92, -v147
	s_waitcnt lgkmcnt(1)
	v_cndmask_b32_e64 v103, 0, v107, s[6:7]
	v_add_f32_e32 v107, v118, v84
	v_mov_b32_e32 v164, v111
	v_mov_b32_e32 v165, v191
	v_add_f32_e32 v83, v83, v107
	v_pk_add_f32 v[106:107], v[106:107], v[164:165] neg_lo:[0,1] neg_hi:[0,1]
	v_mov_b32_e32 v191, v111
	v_mov_b32_e32 v169, v107
	v_add_f32_e32 v84, v106, v107
	v_pk_add_f32 v[106:107], v[168:169], v[190:191] neg_lo:[0,1] neg_hi:[0,1]
	v_add_f32_e32 v91, v91, v103
	v_fma_f32 v121, v99, s92, -v162
	v_add_f32_e32 v99, v106, v107
	ds_bpermute_b32 v186, v180, v91
	v_sub_f32_e32 v91, v91, v123
	v_exp_f32_e32 v123, v99
	ds_bpermute_b32 v99, v178, v119
	v_mov_b32_e32 v105, v107
	v_mov_b32_e32 v111, v190
	v_pk_add_f32 v[104:105], v[104:105], v[110:111] neg_lo:[0,1] neg_hi:[0,1]
	v_mov_b32_e32 v106, v109
	s_waitcnt lgkmcnt(0)
	v_cndmask_b32_e64 v171, v99, 0, s[4:5]
	v_add_f32_e32 v103, v104, v105
	v_pk_add_f32 v[104:105], v[118:119], v[170:171]
	v_exp_f32_e32 v110, v103
	v_add_f32_e32 v103, v104, v91
	v_mov_b32_e32 v107, v147
	v_add_f32_e32 v91, v101, v103
	v_pk_add_f32 v[102:103], v[102:103], v[106:107] neg_lo:[0,1] neg_hi:[0,1]
	v_mov_b32_e32 v147, v109
	v_mov_b32_e32 v101, v103
	v_add_f32_e32 v99, v102, v103
	v_pk_add_f32 v[100:101], v[100:101], v[146:147] neg_lo:[0,1] neg_hi:[0,1]
	v_exp_f32_e32 v102, v99
	v_add_f32_e32 v99, v100, v101
	v_exp_f32_e32 v103, v99
	v_mov_b32_e32 v99, v101
	v_mov_b32_e32 v109, v146
	v_pk_add_f32 v[98:99], v[98:99], v[108:109] neg_lo:[0,1] neg_hi:[0,1]
	ds_bpermute_b32 v106, v179, v105
	v_add_f32_e32 v98, v98, v99
	v_exp_f32_e32 v91, v91
	v_exp_f32_e32 v98, v98
	v_exp_f32_e32 v83, v83
	v_exp_f32_e32 v84, v84
	s_waitcnt lgkmcnt(0)
	v_cndmask_b32_e64 v187, 0, v106, s[6:7]
	v_cvt_pk_bf16_f32 v98, v98, v103
	v_cvt_pk_bf16_f32 v99, v102, v91
	v_pk_add_f32 v[102:103], v[104:105], v[186:187]
	v_cvt_pk_bf16_f32 v101, v84, v83
	v_sub_f32_e32 v84, v103, v119
	v_pk_add_f32 v[106:107], v[102:103], v[84:85] op_sel_hi:[1,0]
	v_max_f32_e32 v145, 0, v90
	v_add_f32_e32 v83, v121, v106
	v_mov_b32_e32 v159, v106
	v_mov_b32_e32 v106, v160
	v_mov_b32_e32 v107, v162
	v_pk_add_f32 v[106:107], v[158:159], v[106:107] neg_lo:[0,1] neg_hi:[0,1]
	v_max_f32_e32 v149, 0, v136
	v_add_f32_e32 v84, v106, v107
	v_mov_b32_e32 v157, v107
	v_pk_mov_b32 v[106:107], v[162:163], v[160:161] op_sel:[1,0]
	v_max_f32_e32 v144, 0, v92
	v_pk_add_f32 v[106:107], v[156:157], v[106:107] neg_lo:[0,1] neg_hi:[0,1]
	v_pk_add_f32 v[108:109], v[148:149], v[150:151]
	v_add_f32_e32 v91, v106, v107
	v_mov_b32_e32 v155, v107
	v_pk_add_f32 v[106:107], v[144:145], v[152:153]
	v_cvt_pk_bf16_f32 v100, v110, v123
	v_pk_add_f32 v[110:111], v[106:107], v[108:109] neg_lo:[1,1] neg_hi:[1,1]
	v_mov_b32_e32 v162, v161
	ds_bpermute_b32 v104, v180, v103
	v_add_f32_e32 v103, v110, v111
	v_pk_add_f32 v[110:111], v[154:155], v[162:163] neg_lo:[0,1] neg_hi:[0,1]
	v_max_f32_e32 v139, 0, v124
	v_max_f32_e32 v87, 0, v126
	v_max_f32_e32 v138, 0, v88
	ds_bpermute_b32 v105, v178, v103
	v_add_f32_e32 v110, v110, v111
	v_exp_f32_e32 v121, v110
	v_pk_add_f32 v[110:111], v[138:139], v[142:143]
	v_pk_add_f32 v[118:119], v[86:87], v[140:141]
	v_exp_f32_e32 v91, v91
	v_pk_add_f32 v[86:87], v[110:111], v[118:119] neg_lo:[1,1] neg_hi:[1,1]
	s_waitcnt lgkmcnt(0)
; __device__ __forceinline__ float shfl_lane(float x, int src_lane) { return __int_as_float(__builtin_amdgcn_ds_bpermute(src_lane << 2, __float_as_int(x))); }
; __device__ __forceinline__ f32x4 mfma16(bf16x8 a, bf16x8 b, f32x4 c) { return __builtin_amdgcn_mfma_f32_16x16x32_bf16(a, b, c, 0, 0, 0); }
; __device__ __forceinline__ float ex2(float x) { return __builtin_amdgcn_exp2f(x); }
; __device__ __forceinline__ void pv_tiles(f32x4 (&o)[8], const bf16_t* Vts, const bf16x8 (&pf)[4], int fr, int g, int tlo, int thi) {
;   __builtin_amdgcn_s_setprio(1);
; #pragma unroll
;   for (int kc = 0; kc < 4; ++kc) {
;     if (2 * kc + 1 >= tlo && 2 * kc <= thi) {
; #pragma unroll
;       for (int dt = 0; dt < 8; ++dt) {
;         const bf16_t* vp = Vts + (dt * 16 + fr) * LROW + kc * 32 + g * 4;
;         bf16x4 lo = *(const bf16x4*)vp, hi = *(const bf16x4*)(vp + 16);
;         bf16x8 a = __builtin_shufflevector(lo, hi, 0, 1, 2, 3, 4, 5, 6, 7);
;         o[dt] = mfma16(a, pf[kc], o[dt]);
;       }
;     }
; __device__ __forceinline__ void sb_item(KParams p, int tb, int hd) {
;     ...
;       for (int T = 7; T >= 0; --T) {
;         if (T <= thi) {
;           const float x = (l1[T][0] + l1[T][1]) + (l1[T][2] + l1[T][3]);
;           float a = shfl_lane(x, (lane + 16) & 63); a = (g < 3) ? a : 0.f;
;           const float y1 = x + a;
;           float b2 = shfl_lane(y1, (lane + 32) & 63); b2 = (g < 2) ? b2 : 0.f;
;           const float incl = y1 + b2;
;           const float tt = shfl_lane(incl, fr);
;           float base = running + (incl - x);
;           const float w3 = ex2(s[T][3] + base); base += l1[T][3];
;           const float w2 = ex2(s[T][2] + base); base += l1[T][2];
;           const float w1 = ex2(s[T][1] + base); base += l1[T][1];
;           const float w0 = ex2(s[T][0] + base);
;           set_pf(pf, T, w0, w1, w2, w3);
;           running += tt;
;         }
;       }
;       carry = running;
;       pv_tiles(o, Vts, pf, fr, g, 0, thi);
	v_cndmask_b32_e64 v105, v105, 0, s[4:5]
	v_add_f32_e32 v125, v86, v87
	ds_bpermute_b32 v127, v178, v125
	v_add_f32_e32 v105, v103, v105
	v_exp_f32_e32 v83, v83
	v_exp_f32_e32 v84, v84
	ds_bpermute_b32 v123, v179, v105
	v_cvt_pk_bf16_f32 v86, v121, v91
	s_waitcnt lgkmcnt(1)
	v_cndmask_b32_e64 v91, v127, 0, s[4:5]
	v_add_f32_e32 v91, v125, v91
	v_max_f32_e32 v131, 0, v82
	v_max_f32_e32 v129, 0, v120
	v_max_f32_e32 v130, 0, v122
	v_cvt_pk_bf16_f32 v87, v84, v83
	v_fma_f32 v83, v93, s92, -v108
	ds_bpermute_b32 v93, v179, v91
	s_waitcnt lgkmcnt(1)
	v_cndmask_b32_e64 v84, 0, v123, s[6:7]
	v_pk_add_f32 v[130:131], v[130:131], v[134:135]
	v_pk_add_f32 v[128:129], v[128:129], v[132:133]
	v_add_f32_e32 v84, v105, v84
	v_pk_add_f32 v[132:133], v[130:131], v[128:129] neg_lo:[1,1] neg_hi:[1,1]
	ds_bpermute_b32 v138, v180, v84
	v_sub_f32_e32 v84, v84, v103
	v_mov_b32_e32 v103, v132
	v_mov_b32_e32 v105, v133
	v_pk_add_f32 v[102:103], v[102:103], v[104:105]
	v_fma_f32 v121, v89, s92, -v118
	s_waitcnt lgkmcnt(1)
	v_cndmask_b32_e64 v89, 0, v93, s[6:7]
	v_add_f32_e32 v93, v102, v84
	v_mov_b32_e32 v104, v106
	v_mov_b32_e32 v105, v108
	v_add_f32_e32 v83, v83, v93
	v_pk_add_f32 v[92:93], v[92:93], v[104:105] neg_lo:[0,1] neg_hi:[0,1]
	v_add_f32_e32 v89, v91, v89
	v_add_f32_e32 v84, v92, v93
	v_mov_b32_e32 v137, v93
	v_pk_mov_b32 v[92:93], v[108:109], v[106:107] op_sel:[1,0]
	v_exp_f32_e32 v123, v84
	v_pk_add_f32 v[92:93], v[136:137], v[92:93] neg_lo:[0,1] neg_hi:[0,1]
	v_mov_b32_e32 v108, v107
	v_add_f32_e32 v84, v92, v93
	ds_bpermute_b32 v92, v178, v103
	v_mov_b32_e32 v91, v93
	v_pk_add_f32 v[90:91], v[90:91], v[108:109] neg_lo:[0,1] neg_hi:[0,1]
	ds_bpermute_b32 v140, v180, v89
	v_sub_f32_e32 v89, v89, v125
	s_waitcnt lgkmcnt(1)
	v_cndmask_b32_e64 v139, v92, 0, s[4:5]
	v_add_f32_e32 v90, v90, v91
	v_pk_add_f32 v[92:93], v[102:103], v[138:139]
	v_exp_f32_e32 v108, v90
	v_add_f32_e32 v89, v92, v89
	v_mov_b32_e32 v90, v110
	v_mov_b32_e32 v91, v118
	v_pk_add_f32 v[104:105], v[88:89], v[90:91] neg_lo:[0,1] neg_hi:[0,1]
	v_pk_mov_b32 v[90:91], v[118:119], v[110:111] op_sel:[1,0]
	v_mov_b32_e32 v127, v105
	v_exp_f32_e32 v83, v83
	v_pk_add_f32 v[90:91], v[126:127], v[90:91] neg_lo:[0,1] neg_hi:[0,1]
	v_mov_b32_e32 v118, v111
	v_mov_b32_e32 v125, v91
	v_pk_add_f32 v[106:107], v[124:125], v[118:119] neg_lo:[0,1] neg_hi:[0,1]
	v_add_f32_e32 v90, v90, v91
	v_add_f32_e32 v88, v106, v107
	v_exp_f32_e32 v88, v88
	v_exp_f32_e32 v90, v90
	v_fma_f32 v91, v85, s92, -v128
	v_cvt_pk_bf16_f32 v85, v123, v83
	ds_bpermute_b32 v83, v179, v93
	v_cvt_pk_bf16_f32 v90, v88, v90
	v_add_f32_e32 v88, v104, v105
	v_exp_f32_e32 v106, v88
	v_add_f32_e32 v88, v121, v89
	s_waitcnt lgkmcnt(0)
	v_cndmask_b32_e64 v141, 0, v83, s[6:7]
	v_exp_f32_e32 v107, v88
	v_pk_add_f32 v[88:89], v[92:93], v[140:141]
	v_mov_b32_e32 v102, v130
	v_sub_f32_e32 v92, v89, v103
	v_pk_add_f32 v[92:93], v[88:89], v[92:93] op_sel_hi:[1,0]
	v_mov_b32_e32 v103, v128
	v_mov_b32_e32 v123, v92
	v_exp_f32_e32 v84, v84
	v_pk_add_f32 v[102:103], v[122:123], v[102:103] neg_lo:[0,1] neg_hi:[0,1]
	v_pk_mov_b32 v[104:105], v[128:129], v[130:131] op_sel:[1,0]
	v_mov_b32_e32 v121, v103
	v_pk_add_f32 v[104:105], v[120:121], v[104:105] neg_lo:[0,1] neg_hi:[0,1]
	v_mov_b32_e32 v128, v131
	v_mov_b32_e32 v83, v105
	v_cvt_pk_bf16_f32 v84, v108, v84
	ds_bpermute_b32 v108, v180, v89
	v_pk_add_f32 v[82:83], v[82:83], v[128:129] neg_lo:[0,1] neg_hi:[0,1]
	v_add_f32_e32 v89, v102, v103
	v_add_f32_e32 v82, v82, v83
	v_add_f32_e32 v83, v104, v105
	v_add_f32_e32 v91, v91, v92
	v_exp_f32_e32 v82, v82
	v_exp_f32_e32 v83, v83
	v_exp_f32_e32 v89, v89
	v_exp_f32_e32 v92, v91
	s_waitcnt lgkmcnt(0)
	v_add_f32_e32 v118, v88, v108
	v_cvt_pk_bf16_f32 v91, v106, v107
	v_cvt_pk_bf16_f32 v88, v82, v83
	v_cvt_pk_bf16_f32 v89, v89, v92
	v_add_u32_e32 v92, 0x8800, v181
	v_add_u32_e32 v93, 0x9800, v181
	v_add_u32_e32 v106, 0xa800, v181
	v_add_u32_e32 v107, 0xb800, v181
	v_add_u32_e32 v108, 0xc800, v181
	v_add_u32_e32 v109, 0xd800, v181
	v_add_u32_e32 v110, 0xe800, v181
	v_add_u32_e32 v111, 0xf800, v181
	ds_read2_b64 v[128:131], v92 offset1:4
	ds_read2_b64 v[132:135], v93 offset0:32 offset1:36
	ds_read2_b64 v[136:139], v106 offset0:64 offset1:68
	ds_read2_b64 v[140:143], v107 offset0:96 offset1:100
	ds_read2_b64 v[144:147], v108 offset0:128 offset1:132
	ds_read2_b64 v[148:151], v109 offset0:160 offset1:164
	ds_read2_b64 v[152:155], v110 offset0:192 offset1:196
	ds_read2_b64 v[156:159], v111 offset0:224 offset1:228
	ds_read2_b64 v[160:163], v92 offset0:8 offset1:12
	ds_read2_b64 v[164:167], v93 offset0:40 offset1:44
	ds_read2_b64 v[168:171], v106 offset0:72 offset1:76
	ds_read2_b64 v[188:191], v107 offset0:104 offset1:108
	s_waitcnt lgkmcnt(11)
; __device__ __forceinline__ f32x4 mfma16(bf16x8 a, bf16x8 b, f32x4 c) { return __builtin_amdgcn_mfma_f32_16x16x32_bf16(a, b, c, 0, 0, 0); }
; __device__ __forceinline__ void pv_tiles(f32x4 (&o)[8], const bf16_t* Vts, const bf16x8 (&pf)[4], int fr, int g, int tlo, int thi) {
;   __builtin_amdgcn_s_setprio(1);
; #pragma unroll
;   for (int kc = 0; kc < 4; ++kc) {
;     if (2 * kc + 1 >= tlo && 2 * kc <= thi) {
; #pragma unroll
;       for (int dt = 0; dt < 8; ++dt) {
;         const bf16_t* vp = Vts + (dt * 16 + fr) * LROW + kc * 32 + g * 4;
;         bf16x4 lo = *(const bf16x4*)vp, hi = *(const bf16x4*)(vp + 16);
;         bf16x8 a = __builtin_shufflevector(lo, hi, 0, 1, 2, 3, 4, 5, 6, 7);
;         o[dt] = mfma16(a, pf[kc], o[dt]);
;       }
;     }
;   }
;   __builtin_amdgcn_s_setprio(0);
	v_mfma_f32_16x16x32_bf16 v[78:81], v[128:131], v[88:91], v[78:81]
	ds_read2_b64 v[128:131], v108 offset0:136 offset1:140
	s_waitcnt lgkmcnt(11)
	v_mfma_f32_16x16x32_bf16 v[74:77], v[132:135], v[88:91], v[74:77]
	ds_read2_b64 v[132:135], v109 offset0:168 offset1:172
	s_waitcnt lgkmcnt(11)
	v_mfma_f32_16x16x32_bf16 v[70:73], v[136:139], v[88:91], v[70:73]
	ds_read2_b64 v[136:139], v110 offset0:200 offset1:204
	s_waitcnt lgkmcnt(11)
	v_mfma_f32_16x16x32_bf16 v[66:69], v[140:143], v[88:91], v[66:69]
	ds_read2_b64 v[140:143], v111 offset0:232 offset1:236
	s_waitcnt lgkmcnt(11)
	v_mfma_f32_16x16x32_bf16 v[62:65], v[144:147], v[88:91], v[62:65]
	ds_read2_b64 v[144:147], v92 offset0:16 offset1:20
	s_waitcnt lgkmcnt(11)
	v_mfma_f32_16x16x32_bf16 v[58:61], v[148:151], v[88:91], v[58:61]
	ds_read2_b64 v[148:151], v93 offset0:48 offset1:52
	s_waitcnt lgkmcnt(11)
	v_mfma_f32_16x16x32_bf16 v[54:57], v[152:155], v[88:91], v[54:57]
	ds_read2_b64 v[152:155], v106 offset0:80 offset1:84
	s_waitcnt lgkmcnt(11)
	v_mfma_f32_16x16x32_bf16 v[50:53], v[156:159], v[88:91], v[50:53]
	ds_read2_b64 v[156:159], v107 offset0:112 offset1:116
	s_waitcnt lgkmcnt(11)
	v_mfma_f32_16x16x32_bf16 v[78:81], v[160:163], v[84:87], v[78:81]
	ds_read2_b64 v[160:163], v108 offset0:144 offset1:148
	s_waitcnt lgkmcnt(11)
	v_mfma_f32_16x16x32_bf16 v[74:77], v[164:167], v[84:87], v[74:77]
	ds_read2_b64 v[164:167], v109 offset0:176 offset1:180
	s_waitcnt lgkmcnt(11)
	v_mfma_f32_16x16x32_bf16 v[70:73], v[168:171], v[84:87], v[70:73]
	ds_read2_b64 v[168:171], v110 offset0:208 offset1:212
	s_waitcnt lgkmcnt(11)
	v_mfma_f32_16x16x32_bf16 v[66:69], v[188:191], v[84:87], v[66:69]
	ds_read2_b64 v[188:191], v111 offset0:240 offset1:244
	s_waitcnt lgkmcnt(11)
	v_mfma_f32_16x16x32_bf16 v[62:65], v[128:131], v[84:87], v[62:65]
	ds_read2_b64 v[128:131], v92 offset0:24 offset1:28
	s_waitcnt lgkmcnt(11)
	v_mfma_f32_16x16x32_bf16 v[58:61], v[132:135], v[84:87], v[58:61]
	ds_read2_b64 v[132:135], v93 offset0:56 offset1:60
	s_waitcnt lgkmcnt(11)
	v_mfma_f32_16x16x32_bf16 v[54:57], v[136:139], v[84:87], v[54:57]
	ds_read2_b64 v[136:139], v106 offset0:88 offset1:92
	s_waitcnt lgkmcnt(11)
	v_mfma_f32_16x16x32_bf16 v[50:53], v[140:143], v[84:87], v[50:53]
	ds_read2_b64 v[140:143], v107 offset0:120 offset1:124
	s_waitcnt lgkmcnt(11)
	v_mfma_f32_16x16x32_bf16 v[78:81], v[144:147], v[98:101], v[78:81]
	ds_read2_b64 v[144:147], v108 offset0:152 offset1:156
	s_waitcnt lgkmcnt(11)
	v_mfma_f32_16x16x32_bf16 v[74:77], v[148:151], v[98:101], v[74:77]
	ds_read2_b64 v[148:151], v109 offset0:184 offset1:188
	s_waitcnt lgkmcnt(11)
	v_mfma_f32_16x16x32_bf16 v[70:73], v[152:155], v[98:101], v[70:73]
	ds_read2_b64 v[152:155], v110 offset0:216 offset1:220
	s_waitcnt lgkmcnt(11)
	v_mfma_f32_16x16x32_bf16 v[66:69], v[156:159], v[98:101], v[66:69]
	ds_read2_b64 v[156:159], v111 offset0:248 offset1:252
	s_waitcnt lgkmcnt(11)
	v_mfma_f32_16x16x32_bf16 v[62:65], v[160:163], v[98:101], v[62:65]
	s_waitcnt lgkmcnt(10)
	v_mfma_f32_16x16x32_bf16 v[58:61], v[164:167], v[98:101], v[58:61]
	s_waitcnt lgkmcnt(9)
	v_mfma_f32_16x16x32_bf16 v[54:57], v[168:171], v[98:101], v[54:57]
	s_waitcnt lgkmcnt(8)
	v_mfma_f32_16x16x32_bf16 v[50:53], v[188:191], v[98:101], v[50:53]
	s_waitcnt lgkmcnt(7)
	v_mfma_f32_16x16x32_bf16 v[78:81], v[128:131], v[94:97], v[78:81]
	s_waitcnt lgkmcnt(6)
	v_mfma_f32_16x16x32_bf16 v[74:77], v[132:135], v[94:97], v[74:77]
	s_waitcnt lgkmcnt(5)
	v_mfma_f32_16x16x32_bf16 v[70:73], v[136:139], v[94:97], v[70:73]
	s_waitcnt lgkmcnt(4)
	v_mfma_f32_16x16x32_bf16 v[66:69], v[140:143], v[94:97], v[66:69]
	s_waitcnt lgkmcnt(3)
	v_mfma_f32_16x16x32_bf16 v[62:65], v[144:147], v[94:97], v[62:65]
	s_waitcnt lgkmcnt(2)
	v_mfma_f32_16x16x32_bf16 v[58:61], v[148:151], v[94:97], v[58:61]
	s_waitcnt lgkmcnt(1)
	v_mfma_f32_16x16x32_bf16 v[54:57], v[152:155], v[94:97], v[54:57]
	s_waitcnt lgkmcnt(0)
	v_mfma_f32_16x16x32_bf16 v[50:53], v[156:159], v[94:97], v[50:53]

; __device__ __forceinline__ void phase_mixers(int l) {
;     ...
;   { KParams p = kparams(); for (int it = blockIdx.x; it < NBLK * 8; it += gridDim.x) sb_item(p, (NBLK - 1) - (it >> 3), it & 7); }
; #pragma unroll 1
;   for (int rep = 0; rep < DUP_SWA; ++rep)
;   { KParams p = kparams(); for (int it = blockIdx.x; it < NBLK * 8; it += gridDim.x) swa_item(p, l, it >> 3, it & 7); }
.LBB0_296:
	s_setprio 0
	v_readlane_b32 s4, v255, 10
	v_readlane_b32 s0, v255, 12
	v_readlane_b32 s5, v255, 11
	v_readlane_b32 s1, v255, 13
	s_and_b64 vcc, exec, s[4:5]
	s_cbranch_vccz .LBB0_416
	v_readlane_b32 s4, v255, 26
	s_lshl_b32 s81, s4, 3
	v_readlane_b32 s82, v255, 14
	s_branch .LBB0_299
